# vG plus NA attention loop: six v_mov_b64 K-fragment copies removed (last three K prefetch loads issued right behind their consuming MFMAs) and back edge rotated to one conditional branch
# speedup vs baseline: 1.0090x; 1.0012x over previous
; template <bool NA>
; __device__ __forceinline__ void attn_unit(const bf16_t* qp, const bf16_t* kp, const bf16_t* vp, int lo, int nblk, int tq, int r, int qc, const LAS float* rpl, float m, float l,
;                                           LAS float* red, int w, int lane, bf16_t* outp) {
;     ...
;     for (int n = 0; n < nblk; ++n) {
;         const int adv = (n + 1 < nblk) ? 4096 : 0;
;         f32x16 s;
; #pragma unroll
;         for (int i = 0; i < 16; ++i) s[i] = 0.f;
; #pragma unroll
;         for (int c = 0; c < 8; ++c) s = __builtin_amdgcn_mfma_f32_32x32x16_bf16(kf[c], qf[c], s, 0, 0, 0);
;         __builtin_amdgcn_sched_barrier(0);
;         kp += adv;
; #pragma unroll
;         for (int c = 0; c < 8; ++c) kf[c] = *(const bf16x8*)(kp + 512 * c);
;         __builtin_amdgcn_sched_barrier(0);
;         const int kblk = lo + n;
;         if (NA) {
;             const int krow = kblk >> 1, kc0 = 32 * (kblk & 1) + 4 * hi;
;             const LAS float* rpr = rpl + (krow - r + 7) * 31 + (kc0 - qc + 15);
;             const int vb = kc0 - cs;
;             float bias[16];
; #pragma unroll
;             for (int i = 0; i < 16; ++i) bias[i] = rpr[8 * (i >> 2) + (i & 3)];
; #pragma unroll
;             for (int i = 0; i < 16; ++i) asm volatile("" : "+v"(bias[i]));
; #pragma unroll
;             for (int i = 0; i < 16; ++i) {
;                 const int off = 8 * (i >> 2) + (i & 3);
;                 s[i] = ((unsigned)(vb + off) < 16u) ? (s[i] + bias[i]) : -INFINITY;
;             }
;         } else if (kblk - (tq >> 5) == -4 || kblk - (tq >> 5) == 4) {
;             const int k0 = kblk * 32 + 4 * hi - tq;
; #pragma unroll
;             for (int i = 0; i < 16; ++i) { const int dlt = k0 + 8 * (i >> 2) + (i & 3); s[i] = (dlt >= -128 && dlt <= 128) ? s[i] : -INFINITY; }
;         }
;         float mx = fmaxf(fmaxf(fmaxf(s[0], s[1]), fmaxf(s[2], s[3])), fmaxf(fmaxf(s[4], s[5]), fmaxf(s[6], s[7])));
;         mx = fmaxf(mx, fmaxf(fmaxf(fmaxf(s[8], s[9]), fmaxf(s[10], s[11])), fmaxf(fmaxf(s[12], s[13]), fmaxf(s[14], s[15]))));
;         mx = fmaxf(mx, shfl_xor_l(mx, 32, lane));
;         const float mn = fmaxf(m, mx);
;         if (__builtin_amdgcn_ballot_w64(mn > m) != 0ull) {
;             const float alpha = __builtin_amdgcn_exp2f(m - mn);
;             l *= alpha;
; #pragma unroll
;             for (int db = 0; db < 4; ++db) o[db] = o[db] * alpha;
.LBB0_160:
	s_waitcnt vmcnt(8)
	s_cmp_eq_u32 s18, 15
	s_cselect_b32 s14, 0, 0x1000
	v_mfma_f32_32x32x16_bf16 v[80:95], v[128:131], v[96:99], 0
	s_lshl_b32 s14, s14, 1
	v_lshl_add_u64 v[202:203], v[202:203], 0, s[14:15]
	v_add_co_u32_e32 v14, vcc, s54, v202
	s_nop 1
	v_addc_co_u32_e32 v15, vcc, 0, v203, vcc
	v_mfma_f32_32x32x16_bf16 v[80:95], v[132:135], v[100:103], v[80:95]
	global_load_dwordx4 v[128:131], v[202:203], off
	global_load_dwordx4 v[132:135], v[202:203], off offset:1024
	v_mfma_f32_32x32x16_bf16 v[80:95], v[136:139], v[104:107], v[80:95]
	v_mfma_f32_32x32x16_bf16 v[80:95], v[140:143], v[108:111], v[80:95]
	global_load_dwordx4 v[136:139], v[202:203], off offset:2048
	global_load_dwordx4 v[140:143], v[202:203], off offset:3072
	v_mfma_f32_32x32x16_bf16 v[80:95], v[160:163], v[112:115], v[80:95]
	global_load_dwordx4 v[160:163], v[14:15], off
	v_mfma_f32_32x32x16_bf16 v[80:95], v[168:171], v[116:119], v[80:95]
	global_load_dwordx4 v[168:171], v[14:15], off offset:1024
	v_mfma_f32_32x32x16_bf16 v[80:95], v[184:187], v[120:123], v[80:95]
	global_load_dwordx4 v[184:187], v[14:15], off offset:2048
	s_lshr_b32 s19, s18, 1
	v_mfma_f32_32x32x16_bf16 v[80:95], v[188:191], v[124:127], v[80:95]
	global_load_dwordx4 v[188:191], v[14:15], off offset:3072
	s_add_i32 s19, s13, s19
	v_and_or_b32 v0, s12, 32, v215
	s_mulk_i32 s19, 0x7c
	s_add_i32 s19, s33, s19
	v_sub_u32_e32 v6, v0, v199
	v_lshl_add_u32 v14, v6, 2, s19
	v_add_u32_e32 v6, 0x14a0, v14
	v_add_u32_e32 v8, 0x14a8, v14
	v_add_u32_e32 v10, 0x14c0, v14
	v_add_u32_e32 v12, 0x14c8, v14
	ds_read2_b32 v[6:7], v6 offset1:1
	ds_read2_b32 v[8:9], v8 offset1:1
	ds_read2_b32 v[10:11], v10 offset1:1
	ds_read2_b32 v[12:13], v12 offset1:1
	v_add_u32_e32 v15, 0x14e0, v14
	v_add_u32_e32 v220, 0x14e8, v14
	v_add_u32_e32 v222, 0x1500, v14
	v_add_u32_e32 v224, 0x1508, v14
	v_sub_u32_e32 v0, v0, v217
	ds_read2_b32 v[14:15], v15 offset1:1
	ds_read2_b32 v[220:221], v220 offset1:1
	ds_read2_b32 v[222:223], v222 offset1:1
	ds_read2_b32 v[224:225], v224 offset1:1
	s_waitcnt lgkmcnt(7)
	v_cmp_gt_u32_e32 vcc, 16, v0
	v_add_f32_e32 v2, v6, v80
	v_add_u32_e32 v3, 1, v0
	v_cndmask_b32_e32 v2, v210, v2, vcc
	v_add_f32_e32 v4, v7, v81
	v_cmp_gt_u32_e32 vcc, 16, v3
	s_waitcnt lgkmcnt(6)
	s_waitcnt lgkmcnt(5)
	s_waitcnt lgkmcnt(4)
	v_cndmask_b32_e32 v3, v210, v4, vcc
	v_add_u32_e32 v4, 2, v0
	v_add_f32_e32 v5, v8, v82
	v_cmp_gt_u32_e32 vcc, 16, v4
	v_add_f32_e32 v6, v9, v83
	v_add_f32_e32 v7, v10, v84
	v_cndmask_b32_e32 v4, v210, v5, vcc
	v_add_u32_e32 v5, 3, v0
	v_cmp_gt_u32_e32 vcc, 16, v5
	v_add_f32_e32 v8, v11, v85
	v_add_f32_e32 v9, v12, v86
	v_cndmask_b32_e32 v5, v210, v6, vcc
	v_add_u32_e32 v6, 8, v0
	v_cmp_gt_u32_e32 vcc, 16, v6
	s_movk_i32 s19, 0xffef
	v_add_f32_e32 v10, v13, v87
	v_cndmask_b32_e32 v6, v210, v7, vcc
	v_add_u32_e32 v7, 9, v0
	v_cmp_gt_u32_e32 vcc, 16, v7
	v_add_u32_e32 v7, 10, v0
	s_waitcnt lgkmcnt(3)
	s_waitcnt lgkmcnt(2)
	v_cndmask_b32_e32 v8, v210, v8, vcc
	v_cmp_gt_u32_e32 vcc, 16, v7
	v_add_u32_e32 v7, 11, v0
	v_add_f32_e32 v12, v15, v89
	v_cndmask_b32_e32 v9, v210, v9, vcc
	v_cmp_gt_u32_e32 vcc, 16, v7
	v_add_f32_e32 v7, v14, v88
	v_add_f32_e32 v13, v220, v90
	v_cndmask_b32_e32 v10, v210, v10, vcc
	v_cmp_lt_u32_e32 vcc, s19, v0
	v_add_f32_e32 v14, v221, v91
	s_waitcnt lgkmcnt(1)
	s_waitcnt lgkmcnt(0)
	v_cndmask_b32_e32 v11, v210, v7, vcc
	v_add_u32_e32 v7, 17, v0
	v_cmp_gt_u32_e32 vcc, 16, v7
	v_add_u32_e32 v7, 18, v0
	v_add_f32_e32 v15, v222, v92
	v_cndmask_b32_e32 v12, v210, v12, vcc
	v_cmp_gt_u32_e32 vcc, 16, v7
	v_add_u32_e32 v7, 19, v0
	v_add_f32_e32 v80, v223, v93
	v_cndmask_b32_e32 v13, v210, v13, vcc
	v_cmp_gt_u32_e32 vcc, 16, v7
	v_add_u32_e32 v7, 24, v0
	v_add_f32_e32 v81, v224, v94
	v_cndmask_b32_e32 v14, v210, v14, vcc
	v_cmp_gt_u32_e32 vcc, 16, v7
	v_add_u32_e32 v7, 25, v0
	v_max_f32_e32 v82, v9, v10
	v_cndmask_b32_e32 v15, v210, v15, vcc
	v_cmp_gt_u32_e32 vcc, 16, v7
	v_add_u32_e32 v7, 26, v0
	v_add_u32_e32 v0, 27, v0
	v_cndmask_b32_e32 v80, v210, v80, vcc
	v_cmp_gt_u32_e32 vcc, 16, v7
	v_add_f32_e32 v7, v225, v95
	v_max_f32_e32 v83, v11, v12
	v_cndmask_b32_e32 v81, v210, v81, vcc
	v_cmp_gt_u32_e32 vcc, 16, v0
	v_max_f32_e32 v0, v4, v5
	v_max_f32_e32 v84, v13, v14
	v_cndmask_b32_e32 v7, v210, v7, vcc
	v_max_f32_e32 v85, v81, v7
	v_max3_f32 v85, v15, v80, v85
	v_max3_f32 v0, v2, v3, v0
	v_max3_f32 v82, v6, v8, v82
	v_max3_f32 v83, v83, v84, v85
	v_max3_f32 v0, v0, v82, v83
	ds_bpermute_b32 v82, v214, v0
	s_waitcnt lgkmcnt(0)
	v_max3_f32 v0, v219, v0, v82
	v_cmp_gt_f32_e32 vcc, v0, v219
	s_cbranch_vccz .LBB0_162
	v_sub_f32_e32 v82, v219, v0
	v_exp_f32_e32 v82, v82
	s_nop 0
	v_pk_mul_f32 v[78:79], v[78:79], v[82:83] op_sel_hi:[1,0]
	v_pk_mul_f32 v[76:77], v[76:77], v[82:83] op_sel_hi:[1,0]
	v_pk_mul_f32 v[74:75], v[74:75], v[82:83] op_sel_hi:[1,0]
	v_pk_mul_f32 v[72:73], v[72:73], v[82:83] op_sel_hi:[1,0]
	v_pk_mul_f32 v[70:71], v[70:71], v[82:83] op_sel_hi:[1,0]
	v_pk_mul_f32 v[68:69], v[68:69], v[82:83] op_sel_hi:[1,0]
	v_pk_mul_f32 v[66:67], v[66:67], v[82:83] op_sel_hi:[1,0]
	v_pk_mul_f32 v[64:65], v[64:65], v[82:83] op_sel_hi:[1,0]
	v_pk_mul_f32 v[62:63], v[62:63], v[82:83] op_sel_hi:[1,0]
	v_pk_mul_f32 v[60:61], v[60:61], v[82:83] op_sel_hi:[1,0]
	v_pk_mul_f32 v[58:59], v[58:59], v[82:83] op_sel_hi:[1,0]
	v_pk_mul_f32 v[56:57], v[56:57], v[82:83] op_sel_hi:[1,0]
	v_pk_mul_f32 v[54:55], v[54:55], v[82:83] op_sel_hi:[1,0]
	v_pk_mul_f32 v[52:53], v[52:53], v[82:83] op_sel_hi:[1,0]
	v_pk_mul_f32 v[50:51], v[50:51], v[82:83] op_sel_hi:[1,0]
	v_pk_mul_f32 v[48:49], v[48:49], v[82:83] op_sel_hi:[1,0]
	v_pk_mul_f32 v[46:47], v[46:47], v[82:83] op_sel_hi:[1,0]
	v_pk_mul_f32 v[44:45], v[44:45], v[82:83] op_sel_hi:[1,0]
	v_pk_mul_f32 v[42:43], v[42:43], v[82:83] op_sel_hi:[1,0]
	v_pk_mul_f32 v[40:41], v[40:41], v[82:83] op_sel_hi:[1,0]
	v_pk_mul_f32 v[38:39], v[38:39], v[82:83] op_sel_hi:[1,0]
	v_pk_mul_f32 v[36:37], v[36:37], v[82:83] op_sel_hi:[1,0]
	v_pk_mul_f32 v[34:35], v[34:35], v[82:83] op_sel_hi:[1,0]
	v_pk_mul_f32 v[32:33], v[32:33], v[82:83] op_sel_hi:[1,0]
	v_pk_mul_f32 v[30:31], v[30:31], v[82:83] op_sel_hi:[1,0]
	v_pk_mul_f32 v[28:29], v[28:29], v[82:83] op_sel_hi:[1,0]
	v_pk_mul_f32 v[26:27], v[26:27], v[82:83] op_sel_hi:[1,0]
	v_pk_mul_f32 v[24:25], v[24:25], v[82:83] op_sel_hi:[1,0]
	v_pk_mul_f32 v[22:23], v[22:23], v[82:83] op_sel_hi:[1,0]
	v_pk_mul_f32 v[20:21], v[20:21], v[82:83] op_sel_hi:[1,0]
	v_pk_mul_f32 v[18:19], v[18:19], v[82:83] op_sel_hi:[1,0]
	v_pk_mul_f32 v[16:17], v[16:17], v[82:83] op_sel_hi:[1,0]
	v_mul_f32_e32 v218, v218, v82
	s_branch .LBB0_163

; __device__ __forceinline__ unsigned cvt_pk_bf16(float lo, float hi) { unsigned r; asm volatile("v_cvt_pk_bf16_f32 %0, %1, %2" : "=v"(r) : "v"(lo), "v"(hi)); return r; }
; template <bool NA>
; __device__ __forceinline__ void attn_unit(const bf16_t* qp, const bf16_t* kp, const bf16_t* vp, int lo, int nblk, int tq, int r, int qc, const LAS float* rpl, float m, float l,
;                                           LAS float* red, int w, int lane, bf16_t* outp) {
;     ...
;         float sum = 0.f;
; #pragma unroll
;         for (int i = 0; i < 16; ++i) { s[i] = __builtin_amdgcn_exp2f(s[i] - m); sum += s[i]; }
;         l += sum;
;         bf16x8 pf[2];
; #pragma unroll
;         for (int j = 0; j < 2; ++j) {
;             u32x4 wv; wv.x = cvt_pk_bf16(s[8 * j + 0], s[8 * j + 1]); wv.y = cvt_pk_bf16(s[8 * j + 2], s[8 * j + 3]); wv.z = cvt_pk_bf16(s[8 * j + 4], s[8 * j + 5]); wv.w = cvt_pk_bf16(s[8 * j + 6], s[8 * j + 7]);
;             pf[j] = __builtin_bit_cast(bf16x8, wv);
;         }
; #pragma unroll
;         for (int db = 0; db < 4; ++db)
; #pragma unroll
;             for (int j = 0; j < 2; ++j) o[db] = __builtin_amdgcn_mfma_f32_32x32x16_bf16(vf[db * 2 + j], pf[j], o[db], 0, 0, 0);
;         __builtin_amdgcn_sched_barrier(0);
;         vp += adv;
; #pragma unroll
;         for (int c = 0; c < 8; ++c) vf[c] = *(const bf16x8*)(vp + 512 * c);
;         __builtin_amdgcn_sched_barrier(0);
.LBB0_163:
	v_sub_f32_e32 v2, v2, v0
	v_exp_f32_e32 v82, v2
	v_sub_f32_e32 v2, v3, v0
	v_exp_f32_e32 v83, v2
	v_sub_f32_e32 v2, v4, v0
	v_exp_f32_e32 v84, v2
	v_sub_f32_e32 v2, v5, v0
	v_exp_f32_e32 v85, v2
	v_sub_f32_e32 v2, v6, v0
	v_exp_f32_e32 v86, v2
	v_sub_f32_e32 v2, v8, v0
	v_exp_f32_e32 v87, v2
	v_sub_f32_e32 v2, v9, v0
	v_exp_f32_e32 v88, v2
	v_sub_f32_e32 v2, v10, v0
	v_exp_f32_e32 v10, v2
	v_sub_f32_e32 v2, v11, v0
	v_exp_f32_e32 v11, v2
	v_sub_f32_e32 v2, v12, v0
	v_exp_f32_e32 v12, v2
	v_sub_f32_e32 v2, v13, v0
	v_exp_f32_e32 v13, v2
	v_sub_f32_e32 v2, v14, v0
	v_exp_f32_e32 v14, v2
	v_sub_f32_e32 v2, v15, v0
	v_exp_f32_e32 v15, v2
	v_sub_f32_e32 v2, v80, v0
	v_exp_f32_e32 v80, v2
	v_cvt_pk_bf16_f32 v2, v82, v83
	v_cvt_pk_bf16_f32 v3, v84, v85
	v_cvt_pk_bf16_f32 v4, v86, v87
	v_cvt_pk_bf16_f32 v5, v88, v10
	v_add_f32_e32 v82, 0, v82
	s_waitcnt vmcnt(15)
	v_mfma_f32_32x32x16_bf16 v[64:79], v[172:175], v[2:5], v[64:79]
	v_add_f32_e32 v82, v83, v82
	v_add_f32_e32 v82, v84, v82
	v_add_f32_e32 v82, v85, v82
	v_add_f32_e32 v82, v86, v82
	v_sub_f32_e32 v6, v81, v0
	v_add_f32_e32 v82, v87, v82
	v_exp_f32_e32 v81, v6
	s_waitcnt vmcnt(13)
	v_mfma_f32_32x32x16_bf16 v[48:63], v[152:155], v[2:5], v[48:63]
	v_sub_f32_e32 v6, v7, v0
	v_add_f32_e32 v82, v88, v82
	v_exp_f32_e32 v89, v6
	v_cvt_pk_bf16_f32 v6, v11, v12
	v_cvt_pk_bf16_f32 v7, v13, v14
	v_cvt_pk_bf16_f32 v8, v15, v80
	v_cvt_pk_bf16_f32 v9, v81, v89
	s_waitcnt vmcnt(11)
	v_mfma_f32_32x32x16_bf16 v[32:47], v[180:183], v[2:5], v[32:47]
	v_add_f32_e32 v10, v10, v82
	v_add_f32_e32 v10, v11, v10
	s_add_i32 s18, s18, 1
	s_waitcnt vmcnt(9)
	v_mfma_f32_32x32x16_bf16 v[16:31], v[164:167], v[2:5], v[16:31]
	v_add_f32_e32 v2, v12, v10
	v_add_f32_e32 v2, v13, v2
	v_add_f32_e32 v2, v14, v2
	v_add_f32_e32 v2, v15, v2
	v_add_f32_e32 v2, v80, v2
	v_add_f32_e32 v2, v81, v2
	v_add_f32_e32 v4, v89, v2
	v_mfma_f32_32x32x16_bf16 v[64:79], v[156:159], v[6:9], v[64:79]
	v_mfma_f32_32x32x16_bf16 v[48:63], v[148:151], v[6:9], v[48:63]
	v_mfma_f32_32x32x16_bf16 v[32:47], v[176:179], v[6:9], v[32:47]
	s_waitcnt vmcnt(8)
	v_mfma_f32_32x32x16_bf16 v[16:31], v[144:147], v[6:9], v[16:31]
	v_lshl_add_u64 v[204:205], v[204:205], 0, s[14:15]
	v_add_co_u32_e32 v2, vcc, 0x1000, v204
	global_load_dwordx4 v[172:175], v[204:205], off
	global_load_dwordx4 v[156:159], v[204:205], off offset:1024
	global_load_dwordx4 v[152:155], v[204:205], off offset:2048
	global_load_dwordx4 v[148:151], v[204:205], off offset:3072
	v_addc_co_u32_e32 v3, vcc, 0, v205, vcc
	global_load_dwordx4 v[180:183], v[2:3], off
	global_load_dwordx4 v[176:179], v[2:3], off offset:1024
	global_load_dwordx4 v[164:167], v[2:3], off offset:2048
	global_load_dwordx4 v[144:147], v[2:3], off offset:3072
	v_add_f32_e32 v218, v218, v4
	v_mov_b32_e32 v219, v0
	s_add_i32 s12, s12, 32
	s_cmp_lg_u32 s18, 16
	s_cbranch_scc1 .LBB0_160

; #define LAS __attribute__((address_space(3)))
; __global__ void __launch_bounds__(NTHREADS, 2) fwd_kernel(Args a) {
;     ...
; #pragma unroll 1
;             for (int u0 = bid; u0 < 512; u0 += G, ++ucount) {
;                 const int u = (G == 256) ? ((u0 & ~255) + (u0 & 7) * 32 + ((u0 & 255) >> 3)) : u0;
;                 LAS float* red = redbase + (ucount & 1) * 256;
;                 if (u < 256) {
;                     const int r = u >> 1, h = u & 1;
;                     const int qc = 32 * h + ql, tq = r * 64 + qc;
;                     const int lo = 2 * min(max(r - 4, 0), 120);
;                     const size_t fo = ((size_t)(w * 256 + lo) * 8) * 512 + lane * 8;
;                     attn_unit<true>(proj + (size_t)tq * PW + w * 128 + 8 * hi, K2 + fo, V2 + fo, lo, 16, tq, r, qc, rpl, -1e30f, 0.f, red, w, lane, on + (size_t)tq * D + w * 128);
;                 } else {
;                     const int qb = u - 256, tq = qb * 32 + ql, kvh = w >> 2;
;                     const int lo = max(qb - 4, 0), hb = min(qb + 4, 255);
;                     const size_t fo = ((size_t)((8 + kvh) * 256 + lo) * 8) * 512 + lane * 8;
;                     attn_unit<false>(proj + (size_t)tq * PW + 3072 + w * 128 + 8 * hi, K2 + fo, V2 + fo, lo, hb - lo + 1, tq, 0, 0, rpl, sink[layer * 8 + w] * LOG2E, (hi == 0) ? 1.0f : 0.0f, red, w, lane,
;                                      on + (size_t)tq * D + 1024 + w * 128);
;                 }
;             }
;         }
.LBB0_167:
	s_setprio 0
	s_nop 0
	s_nop 0
	s_nop 0
	s_nop 0
	s_nop 0
	s_nop 0
	s_nop 0
	s_nop 0
	s_nop 0
	s_nop 0
	s_nop 0
	s_nop 0
	s_nop 0
	s_nop 0
	s_nop 0
	s_nop 0
	s_nop 0
	s_nop 0
	s_nop 0
	s_nop 0
	s_nop 0
	s_nop 0
	s_mov_b64 s[10:11], 0
